# adaLN pass 1 token loop: next token's activation row prefetched into spare registers behind the parameter loads (software prefetch, one HBM latency overlapped per token)
# baseline (speedup 1.0000x reference)
.LBB0_602:
	s_or_b64 exec, exec, s[12:13]
	s_mov_b64 s[14:15], s[60:61]
	v_mov_b32_e32 v0, v172
	s_waitcnt lgkmcnt(0)
	v_mov_b32_e32 v2, v172
	s_barrier
	s_mov_b32 s4, s94
	v_ashrrev_i32_e32 v2, 6, v2
	s_movk_i32 s2, 0x4800
	v_lshl_add_u32 v6, s4, 3, v2
	v_cmp_gt_i32_e32 vcc, s2, v6
	s_and_saveexec_b64 s[12:13], vcc
	s_cbranch_execz .LBB0_609
	s_load_dwordx4 s[44:47], s[14:15], 0x128
	s_load_dwordx2 s[6:7], s[14:15], 0x30
	v_lshlrev_b32_e32 v0, 2, v0
	v_and_b32_e32 v2, 0xfc, v0
	v_readlane_b32 s2, v255, 48
	s_waitcnt lgkmcnt(0)
	s_add_u32 s14, s46, 0x2a00000
	s_addc_u32 s15, s47, 0
	v_xor_b32_e32 v0, 32, v181
	v_readlane_b32 s3, v255, 49
	s_add_u32 s4, s46, s2
	v_cmp_lt_i32_e32 vcc, v0, v182
	s_addc_u32 s10, s47, s3
	v_readlane_b32 s2, v255, 46
	v_cndmask_b32_e32 v0, v181, v0, vcc
	v_cmp_lt_i32_e32 vcc, v183, v182
	s_add_u32 s16, s4, 0x5603000
	v_readlane_b32 s3, v255, 47
	v_lshlrev_b32_e32 v30, 2, v0
	v_cndmask_b32_e32 v0, v181, v183, vcc
	v_cmp_lt_i32_e32 vcc, v189, v182
	s_addc_u32 s17, s10, 0
	s_lshl_b64 s[10:11], s[2:3], 2
	v_lshlrev_b32_e32 v31, 2, v0
	v_cndmask_b32_e32 v0, v181, v189, vcc
	v_cmp_lt_i32_e32 vcc, v190, v182
	s_add_u32 s4, s6, s10
	v_lshlrev_b32_e32 v32, 2, v0
	v_cndmask_b32_e32 v0, v181, v190, vcc
	v_cmp_lt_i32_e32 vcc, v191, v182
	s_addc_u32 s7, s7, s11
	v_lshlrev_b32_e32 v33, 2, v0
	v_cndmask_b32_e32 v0, v181, v191, vcc
	v_cmp_lt_i32_e32 vcc, v188, v182
	s_add_u32 s6, s4, 0x1000
	v_lshlrev_b32_e32 v34, 2, v0
	v_cndmask_b32_e32 v0, v181, v188, vcc
	s_addc_u32 s7, s7, 0
	v_lshlrev_b32_e32 v35, 2, v0
	v_lshlrev_b32_e32 v0, 2, v2
	v_or_b32_e32 v4, 0x100, v2
	v_lshl_add_u64 v[8:9], s[6:7], 0, v[0:1]
	v_lshlrev_b32_e32 v0, 2, v4
	v_or_b32_e32 v20, 0x200, v2
	v_lshl_add_u64 v[10:11], s[6:7], 0, v[0:1]
	v_lshlrev_b32_e32 v0, 2, v20
	v_or_b32_e32 v22, 0x300, v2
	v_lshl_add_u64 v[12:13], s[6:7], 0, v[0:1]
	v_lshlrev_b32_e32 v0, 2, v22
	v_lshl_add_u64 v[14:15], s[6:7], 0, v[0:1]
	v_lshlrev_b32_e32 v0, 1, v2
	v_lshl_add_u64 v[16:17], s[46:47], 0, v[0:1]
	s_mov_b64 s[2:3], 0x3200000
	v_lshl_add_u64 v[16:17], v[16:17], 0, s[2:3]
	s_mov_b64 s[18:19], 0
	v_lshlrev_b32_e32 v0, 2, v2
	v_lshlrev_b32_e32 v18, 2, v4
	v_lshlrev_b32_e32 v20, 2, v20
	v_lshlrev_b32_e32 v22, 2, v22
	v_min_i32_e32 v132, s29, v6
	v_cmp_lt_i32_e32 vcc, s97, v132
	v_add_u32_e32 v133, 0xffffc000, v132
	v_mov_b32_e32 v134, s14
	v_mov_b32_e32 v135, s15
	v_mov_b32_e32 v136, s44
	v_mov_b32_e32 v137, s45
	v_cndmask_b32_e32 v132, v132, v133, vcc
	v_cndmask_b32_e32 v134, v136, v134, vcc
	v_cndmask_b32_e32 v135, v137, v135, vcc
	v_mov_b32_e32 v133, 0
	v_lshlrev_b64 v[132:133], 12, v[132:133]
	v_lshl_add_u64 v[132:133], v[134:135], 0, v[132:133]
	v_lshl_add_u64 v[132:133], v[132:133], 0, v[0:1]
	global_load_dwordx4 v[114:117], v[132:133], off
	global_load_dwordx4 v[118:121], v[132:133], off offset:1024
	global_load_dwordx4 v[122:125], v[132:133], off offset:2048
	global_load_dwordx4 v[126:129], v[132:133], off offset:3072
	s_waitcnt vmcnt(0)
	s_branch .LBB0_605
.LBB0_604:
	s_or_b64 exec, exec, s[46:47]
	s_waitcnt vmcnt(4)
	v_mov_b32_e32 v36, v114
	v_mov_b32_e32 v37, v115
	v_mov_b32_e32 v38, v116
	v_mov_b32_e32 v39, v117
	v_mov_b32_e32 v40, v118
	v_mov_b32_e32 v41, v119
	v_mov_b32_e32 v42, v120
	v_mov_b32_e32 v43, v121
	v_mov_b32_e32 v44, v122
	v_mov_b32_e32 v45, v123
	v_mov_b32_e32 v46, v124
	v_mov_b32_e32 v47, v125
	v_mov_b32_e32 v2, v126
	v_mov_b32_e32 v3, v127
	v_mov_b32_e32 v4, v128
	v_mov_b32_e32 v5, v129
	s_nop 0
	s_nop 0
	global_load_dwordx4 v[48:51], v[8:9], off
	global_load_dwordx4 v[78:81], v[10:11], off
	global_load_dwordx4 v[90:93], v[12:13], off
	global_load_dwordx4 v[102:105], v[14:15], off
	v_min_i32_e32 v19, 0x4000, v6
	v_ashrrev_i32_e32 v19, 11, v19
	v_mul_hi_i32_i24_e32 v25, 0x9000, v19
	v_mul_i32_i24_e32 v24, 0x9000, v19
	v_lshl_add_u64 v[24:25], s[16:17], 0, v[24:25]
	v_lshl_add_u64 v[26:27], v[24:25], 0, s[38:39]
	v_lshl_add_u64 v[28:29], v[26:27], 0, v[0:1]
	global_load_dwordx4 v[52:55], v[28:29], off
	global_load_dwordx4 v[82:85], v[28:29], off offset:1024
	global_load_dwordx4 v[94:97], v[28:29], off offset:2048
	global_load_dwordx4 v[106:109], v[28:29], off offset:3072
	v_lshl_add_u64 v[28:29], v[24:25], 0, v[0:1]
	global_load_dwordx4 v[56:59], v[28:29], off
	global_load_dwordx4 v[86:89], v[28:29], off offset:1024
	global_load_dwordx4 v[98:101], v[28:29], off offset:2048
	global_load_dwordx4 v[110:113], v[28:29], off offset:3072
	v_lshl_add_u32 v132, s42, 3, v6
	v_min_i32_e32 v132, s29, v132
	v_cmp_lt_i32_e32 vcc, s97, v132
	v_add_u32_e32 v133, 0xffffc000, v132
	v_mov_b32_e32 v134, s14
	v_mov_b32_e32 v135, s15
	v_mov_b32_e32 v136, s44
	v_mov_b32_e32 v137, s45
	v_cndmask_b32_e32 v132, v132, v133, vcc
	v_cndmask_b32_e32 v134, v136, v134, vcc
	v_cndmask_b32_e32 v135, v137, v135, vcc
	v_mov_b32_e32 v133, 0
	v_lshlrev_b64 v[132:133], 12, v[132:133]
	v_lshl_add_u64 v[132:133], v[134:135], 0, v[132:133]
	v_lshl_add_u64 v[132:133], v[132:133], 0, v[0:1]
	global_load_dwordx4 v[114:117], v[132:133], off
	global_load_dwordx4 v[118:121], v[132:133], off offset:1024
	global_load_dwordx4 v[122:125], v[132:133], off offset:2048
	global_load_dwordx4 v[126:129], v[132:133], off offset:3072
	s_mov_b32 s4, s42
	v_mov_b32_e32 v60, v37
	v_mov_b32_e32 v61, v41
	v_mov_b32_e32 v24, v36
	v_mov_b32_e32 v25, v40
	v_mov_b32_e32 v68, v45
	v_mov_b32_e32 v69, v3
	v_pk_mul_f32 v[60:61], v[60:61], v[60:61]
	v_mov_b32_e32 v62, v38
	v_mov_b32_e32 v63, v42
	v_mov_b32_e32 v66, v44
	v_mov_b32_e32 v67, v2
	v_pk_mul_f32 v[68:69], v[68:69], v[68:69]
	v_pk_fma_f32 v[24:25], v[24:25], v[24:25], v[60:61]
	v_mov_b32_e32 v64, v39
	v_mov_b32_e32 v65, v43
	v_mov_b32_e32 v70, v46
	v_mov_b32_e32 v71, v4
	v_pk_fma_f32 v[60:61], v[66:67], v[66:67], v[68:69]
	v_pk_fma_f32 v[24:25], v[62:63], v[62:63], v[24:25]
	v_mov_b32_e32 v72, v47
	v_mov_b32_e32 v73, v5
	v_pk_fma_f32 v[60:61], v[70:71], v[70:71], v[60:61]
	v_pk_fma_f32 v[24:25], v[64:65], v[64:65], v[24:25]
	v_pk_fma_f32 v[60:61], v[72:73], v[72:73], v[60:61]
	v_add_f32_e32 v19, v24, v25
	v_add_f32_e32 v19, v19, v60
	v_add_f32_e32 v19, v19, v61
	ds_bpermute_b32 v21, v30, v19
	v_lshlrev_b64 v[24:25], 11, v[6:7]
	s_waitcnt vmcnt(15)
	v_mov_b32_e32 v60, v48
	v_mov_b32_e32 v48, v36
	v_mov_b32_e32 v36, v37
	s_waitcnt lgkmcnt(0)
	v_add_f32_e32 v19, v19, v21
	ds_bpermute_b32 v21, v31, v19
	v_mov_b32_e32 v37, v39
	s_waitcnt vmcnt(7)
	v_mov_b32_e32 v62, v56
	v_mov_b32_e32 v61, v50
	v_mov_b32_e32 v50, v49
	s_waitcnt lgkmcnt(0)
	v_add_f32_e32 v21, v19, v21
	v_mov_b32_e32 v49, v38
	v_mov_b32_e32 v39, v54
	v_mov_b32_e32 v54, v53
	v_mov_b32_e32 v38, v52
	s_waitcnt lgkmcnt(0)
	s_nop 1
	v_add_f32_dpp v7, v21, v21 row_ror:8 row_mask:0xf bank_mask:0xf bound_ctrl:1
	v_mov_b32_e32 v63, v58
	v_mov_b32_e32 v58, v57
	v_pk_add_f32 v[52:53], v[54:55], 1.0 op_sel_hi:[1,0]
	v_pk_add_f32 v[38:39], v[38:39], 1.0 op_sel_hi:[1,0]
	s_waitcnt lgkmcnt(0)
	s_nop 1
	v_add_f32_dpp v7, v7, v7 row_ror:4 row_mask:0xf bank_mask:0xf bound_ctrl:1
	v_lshl_add_u64 v[24:25], v[16:17], 0, v[24:25]
	v_mov_b32_e32 v19, v1
	s_waitcnt lgkmcnt(0)
	s_nop 1
	v_add_f32_dpp v7, v7, v7 quad_perm:[2,3,0,1] row_mask:0xf bank_mask:0xf bound_ctrl:1
	s_waitcnt lgkmcnt(0)
	s_nop 1
	v_add_f32_dpp v7, v7, v7 quad_perm:[1,0,3,2] row_mask:0xf bank_mask:0xf bound_ctrl:1
	v_fmamk_f32 v7, v7, 0x3a800000, v174
	v_mul_f32_e32 v21, 0x4b800000, v7
	v_cmp_gt_f32_e32 vcc, s27, v7
	s_nop 1
	v_cndmask_b32_e32 v7, v7, v21, vcc
	v_rsq_f32_e32 v7, v7
	s_nop 0
	v_mul_f32_e32 v21, 0x45800000, v7
	v_cndmask_b32_e32 v56, v7, v21, vcc
	v_pk_mul_f32 v[36:37], v[36:37], v[56:57] op_sel_hi:[1,0]
	v_pk_mul_f32 v[48:49], v[48:49], v[56:57] op_sel_hi:[1,0]
	v_pk_mul_f32 v[36:37], v[50:51], v[36:37]
	v_pk_mul_f32 v[48:49], v[60:61], v[48:49]
	v_pk_fma_f32 v[36:37], v[52:53], v[36:37], v[58:59]
	v_pk_fma_f32 v[38:39], v[38:39], v[48:49], v[62:63]
	v_cvt_pk_bf16_f32 v21, v38, v36
	v_cvt_pk_bf16_f32 v37, v39, v37
	v_mov_b32_e32 v36, v21
	global_store_dwordx2 v[24:25], v[36:37], off
	v_lshl_add_u64 v[48:49], v[26:27], 0, v[18:19]
	s_waitcnt vmcnt(5)
	v_mov_b32_e32 v52, v86
	v_mov_b32_e32 v53, v87
	v_mov_b32_e32 v54, v88
	v_mov_b32_e32 v55, v89
	v_mov_b32_e32 v48, v82
	v_mov_b32_e32 v49, v83
	v_mov_b32_e32 v50, v84
	v_mov_b32_e32 v51, v85
	v_mov_b32_e32 v36, v78
	v_mov_b32_e32 v37, v79
	v_mov_b32_e32 v38, v80
	v_mov_b32_e32 v39, v81
	v_mov_b32_e32 v58, v40
	v_mov_b32_e32 v59, v42
	v_mov_b32_e32 v42, v41
	v_pk_mul_f32 v[40:41], v[58:59], v[56:57] op_sel_hi:[1,0]
	v_pk_mul_f32 v[42:43], v[42:43], v[56:57] op_sel_hi:[1,0]
	v_mov_b32_e32 v21, v1
	v_mov_b32_e32 v58, v36
	v_mov_b32_e32 v59, v38
	v_mov_b32_e32 v60, v48
	v_mov_b32_e32 v61, v50
	v_mov_b32_e32 v38, v37
	v_mov_b32_e32 v50, v49
	v_mov_b32_e32 v62, v52
	v_mov_b32_e32 v63, v54
	v_mov_b32_e32 v54, v53
	v_pk_mul_f32 v[36:37], v[40:41], v[58:59]
	v_pk_add_f32 v[40:41], v[60:61], 1.0 op_sel_hi:[1,0]
	v_pk_mul_f32 v[38:39], v[42:43], v[38:39]
	v_pk_add_f32 v[42:43], v[50:51], 1.0 op_sel_hi:[1,0]
	v_pk_fma_f32 v[36:37], v[36:37], v[40:41], v[62:63]
	v_pk_fma_f32 v[38:39], v[38:39], v[42:43], v[54:55]
	v_cvt_pk_bf16_f32 v19, v36, v38
	v_cvt_pk_bf16_f32 v37, v37, v39
	v_mov_b32_e32 v36, v19
	global_store_dwordx2 v[24:25], v[36:37], off offset:512
	v_lshl_add_u64 v[40:41], v[26:27], 0, v[20:21]
	v_mov_b32_e32 v48, v98
	v_mov_b32_e32 v49, v99
	v_mov_b32_e32 v50, v100
	v_mov_b32_e32 v51, v101
	v_mov_b32_e32 v40, v94
	v_mov_b32_e32 v41, v95
	v_mov_b32_e32 v42, v96
	v_mov_b32_e32 v43, v97
	v_mov_b32_e32 v36, v90
	v_mov_b32_e32 v37, v91
	v_mov_b32_e32 v38, v92
	v_mov_b32_e32 v39, v93
	v_mov_b32_e32 v52, v44
	v_mov_b32_e32 v53, v46
	v_mov_b32_e32 v44, v45
	v_mov_b32_e32 v45, v47
	v_pk_mul_f32 v[46:47], v[52:53], v[56:57] op_sel_hi:[1,0]
	v_pk_mul_f32 v[44:45], v[44:45], v[56:57] op_sel_hi:[1,0]
	v_mov_b32_e32 v23, v1
	v_lshl_add_u64 v[26:27], v[26:27], 0, v[22:23]
	v_mov_b32_e32 v52, v36
	v_mov_b32_e32 v53, v38
	v_mov_b32_e32 v54, v40
	v_mov_b32_e32 v55, v42
	v_mov_b32_e32 v38, v37
	v_mov_b32_e32 v42, v41
	v_mov_b32_e32 v58, v48
	v_mov_b32_e32 v59, v50
	v_mov_b32_e32 v50, v49
	v_pk_mul_f32 v[36:37], v[46:47], v[52:53]
	v_pk_add_f32 v[40:41], v[54:55], 1.0 op_sel_hi:[1,0]
	v_pk_mul_f32 v[38:39], v[44:45], v[38:39]
	v_pk_add_f32 v[42:43], v[42:43], 1.0 op_sel_hi:[1,0]
	v_pk_fma_f32 v[36:37], v[36:37], v[40:41], v[58:59]
	v_pk_fma_f32 v[38:39], v[38:39], v[42:43], v[50:51]
	v_cvt_pk_bf16_f32 v19, v36, v38
	v_cvt_pk_bf16_f32 v37, v37, v39
	v_mov_b32_e32 v36, v19
	global_store_dwordx2 v[24:25], v[36:37], off offset:1024
	v_mov_b32_e32 v26, v110
	v_mov_b32_e32 v27, v111
	v_mov_b32_e32 v28, v112
	v_mov_b32_e32 v29, v113
	v_mov_b32_e32 v40, v106
	v_mov_b32_e32 v41, v107
	v_mov_b32_e32 v42, v108
	v_mov_b32_e32 v43, v109
	v_mov_b32_e32 v36, v102
	v_mov_b32_e32 v37, v103
	v_mov_b32_e32 v38, v104
	v_mov_b32_e32 v39, v105
	v_mov_b32_e32 v44, v2
	v_mov_b32_e32 v45, v4
	v_mov_b32_e32 v4, v3
	v_pk_mul_f32 v[2:3], v[44:45], v[56:57] op_sel_hi:[1,0]
	v_pk_mul_f32 v[4:5], v[4:5], v[56:57] op_sel_hi:[1,0]
	v_mov_b32_e32 v47, v42
	v_mov_b32_e32 v45, v38
	v_mov_b32_e32 v38, v37
	v_mov_b32_e32 v42, v41
	v_mov_b32_e32 v44, v36
	v_mov_b32_e32 v46, v40
	v_mov_b32_e32 v49, v28
	v_mov_b32_e32 v28, v27
	v_pk_mul_f32 v[4:5], v[4:5], v[38:39]
	v_pk_add_f32 v[36:37], v[42:43], 1.0 op_sel_hi:[1,0]
	v_mov_b32_e32 v48, v26
	v_pk_mul_f32 v[2:3], v[2:3], v[44:45]
	v_pk_add_f32 v[26:27], v[46:47], 1.0 op_sel_hi:[1,0]
	v_pk_fma_f32 v[4:5], v[4:5], v[36:37], v[28:29]
	v_pk_fma_f32 v[2:3], v[2:3], v[26:27], v[48:49]
	v_and_b32_sdwa v21, v5, v177 dst_sel:DWORD dst_unused:UNUSED_PAD src0_sel:WORD_1 src1_sel:DWORD
	v_and_b32_sdwa v23, v4, v177 dst_sel:DWORD dst_unused:UNUSED_PAD src0_sel:WORD_1 src1_sel:DWORD
	v_and_b32_sdwa v7, v3, v177 dst_sel:DWORD dst_unused:UNUSED_PAD src0_sel:WORD_1 src1_sel:DWORD
	v_and_b32_sdwa v19, v2, v177 dst_sel:DWORD dst_unused:UNUSED_PAD src0_sel:WORD_1 src1_sel:DWORD
	v_add3_u32 v5, v5, v21, s28
	v_add3_u32 v4, v4, v23, s28
	v_add3_u32 v2, v2, v19, s28
	v_add3_u32 v3, v3, v7, s28
	v_and_b32_e32 v5, 0xffff0000, v5
	v_and_b32_e32 v4, 0xffff0000, v4
	v_or_b32_sdwa v3, v5, v3 dst_sel:DWORD dst_unused:UNUSED_PAD src0_sel:DWORD src1_sel:WORD_1
	v_or_b32_sdwa v2, v4, v2 dst_sel:DWORD dst_unused:UNUSED_PAD src0_sel:DWORD src1_sel:WORD_1
	global_store_dwordx2 v[24:25], v[2:3], off offset:1536
	s_nop 0
	v_lshl_add_u32 v6, s4, 3, v6
	v_cmp_lt_i32_e32 vcc, s29, v6
	s_or_b64 s[18:19], vcc, s[18:19]
	s_andn2_b64 exec, exec, s[18:19]
	s_cbranch_execz .LBB0_609
